# GEMM residual epilogue (down-proj FFN2 and w_out copies): 16 residual loads per tile issued together into dedicated registers, per-step vmcnt(0) replaced by vmcnt(15)
# baseline (speedup 1.0000x reference)
; #define MFMA16(a, b, c) __builtin_amdgcn_mfma_f32_16x16x32_bf16((a), (b), (c), 0, 0, 0)
; template <int EPI>
; DI void gemm_epilogue(f32x4 (&acc)[4][4], int m0, int n0, int wm, int wn, int l15, int quad, const EpiArgs& e) {
;     ...
;     } else {
;       float4 rv[4];
; #pragma unroll
;       for (int nt = 0; nt < 4; ++nt) rv[nt] = *(const float4*)(e.resid + row * D_ + n0 + wn * 64 + nt * 16 + 4 * quad);
; #pragma unroll
;       for (int nt = 0; nt < 4; ++nt) { const f32x4 a = acc[mt][nt];
;         *(float4*)(e.of32 + row * D_ + n0 + wn * 64 + nt * 16 + 4 * quad) = (float4){e.alpha * rv[nt].x + e.sc * a[0], e.alpha * rv[nt].y + e.sc * a[1], e.alpha * rv[nt].z + e.sc * a[2], e.alpha * rv[nt].w + e.sc * a[3]}; }
; DI void gemm_compute_sw(const bf16_t* sb, int wm, int wn, int l15, int quad, f32x4 (&acc)[4][4]) {
; #pragma unroll
;   for (int ks = 0; ks < 2; ++ks) {
;     bf16x8 af[4], bfr[4];
;     const int sl = ((ks * 4 + quad) ^ ((l15 >> 1) & 7)) * 8;
; #pragma unroll
;     for (int mt = 0; mt < 4; ++mt) af[mt] = *(const bf16x8*)(sb + (wm * 64 + mt * 16 + l15) * 64 + sl);
; #pragma unroll
;     for (int nt = 0; nt < 4; ++nt) bfr[nt] = *(const bf16x8*)(sb + 8192 + (wn * 64 + nt * 16 + l15) * 64 + sl);
; #pragma unroll
;     for (int mt = 0; mt < 4; ++mt)
; #pragma unroll
;       for (int nt = 0; nt < 4; ++nt) acc[mt][nt] = MFMA16(bfr[nt], af[mt], acc[mt][nt]);
;   }
; }
.LBB0_65:
	ds_read_b128 v[80:83], v76 offset:49152
	ds_read_b128 v[84:87], v75 offset:32768
	ds_read_b128 v[88:91], v76 offset:51200
	ds_read_b128 v[92:95], v76 offset:53248
	ds_read_b128 v[96:99], v76 offset:55296
	s_add_i32 s0, s0, 2
	s_waitcnt lgkmcnt(0)
	v_mfma_f32_16x16x32_bf16 v[16:19], v[80:83], v[84:87], v[16:19]
	s_cmp_lg_u32 s0, 44
	ds_read_b128 v[112:115], v78 offset:49152
	ds_read_b128 v[116:119], v78 offset:51200
	v_mfma_f32_16x16x32_bf16 v[4:7], v[88:91], v[84:87], v[4:7]
	ds_read_b128 v[120:123], v78 offset:55296
	v_mfma_f32_16x16x32_bf16 v[8:11], v[92:95], v[84:87], v[8:11]
	v_mfma_f32_16x16x32_bf16 v[12:15], v[96:99], v[84:87], v[12:15]
	ds_read_b128 v[84:87], v75 offset:34816
	s_waitcnt lgkmcnt(0)
	v_mfma_f32_16x16x32_bf16 v[0:3], v[80:83], v[84:87], v[0:3]
	v_mfma_f32_16x16x32_bf16 v[20:23], v[88:91], v[84:87], v[20:23]
	v_mfma_f32_16x16x32_bf16 v[24:27], v[92:95], v[84:87], v[24:27]
	v_mfma_f32_16x16x32_bf16 v[28:31], v[96:99], v[84:87], v[28:31]
	ds_read_b128 v[84:87], v75 offset:36864
	s_waitcnt lgkmcnt(0)
	v_mfma_f32_16x16x32_bf16 v[100:103], v[80:83], v[84:87], v[32:35]
	s_nop 2
	ds_read_b128 v[32:35], v75 offset:38912
	v_mfma_f32_16x16x32_bf16 v[104:107], v[88:91], v[84:87], v[36:39]
	v_mfma_f32_16x16x32_bf16 v[108:111], v[92:95], v[84:87], v[44:47]
	v_mfma_f32_16x16x32_bf16 v[84:87], v[96:99], v[84:87], v[52:55]
	s_waitcnt lgkmcnt(0)
	v_mfma_f32_16x16x32_bf16 v[80:83], v[80:83], v[32:35], v[40:43]
	v_mfma_f32_16x16x32_bf16 v[88:91], v[88:91], v[32:35], v[48:51]
	v_mfma_f32_16x16x32_bf16 v[92:95], v[92:95], v[32:35], v[60:63]
	v_mfma_f32_16x16x32_bf16 v[96:99], v[96:99], v[32:35], v[56:59]
	ds_read_b128 v[32:35], v77 offset:32768
	s_waitcnt lgkmcnt(0)
	v_mfma_f32_16x16x32_bf16 v[56:59], v[116:119], v[32:35], v[4:7]
	s_nop 2
	ds_read_b128 v[4:7], v78 offset:53248
	s_waitcnt lgkmcnt(0)
	v_mfma_f32_16x16x32_bf16 v[52:55], v[4:7], v[32:35], v[8:11]
	s_nop 2
	ds_read_b128 v[8:11], v77 offset:34816
	s_waitcnt lgkmcnt(0)
	v_mfma_f32_16x16x32_bf16 v[44:47], v[112:115], v[8:11], v[0:3]
	s_nop 2
	ds_read_b128 v[0:3], v77 offset:36864
	v_mfma_f32_16x16x32_bf16 v[60:63], v[112:115], v[32:35], v[16:19]
	v_mfma_f32_16x16x32_bf16 v[48:51], v[120:123], v[32:35], v[12:15]
	v_mfma_f32_16x16x32_bf16 v[40:43], v[116:119], v[8:11], v[20:23]
	v_mfma_f32_16x16x32_bf16 v[36:39], v[4:7], v[8:11], v[24:27]
	v_mfma_f32_16x16x32_bf16 v[32:35], v[120:123], v[8:11], v[28:31]
	s_waitcnt lgkmcnt(0)
	v_mfma_f32_16x16x32_bf16 v[28:31], v[112:115], v[0:3], v[100:103]
	v_mfma_f32_16x16x32_bf16 v[24:27], v[116:119], v[0:3], v[104:107]
	v_mfma_f32_16x16x32_bf16 v[20:23], v[4:7], v[0:3], v[108:111]
	v_mfma_f32_16x16x32_bf16 v[16:19], v[120:123], v[0:3], v[84:87]
	ds_read_b128 v[0:3], v77 offset:38912
	s_waitcnt vmcnt(0)
	s_waitcnt vmcnt(0) lgkmcnt(0)
	v_mfma_f32_16x16x32_bf16 v[12:15], v[112:115], v[0:3], v[80:83]
	s_barrier
	v_mfma_f32_16x16x32_bf16 v[8:11], v[116:119], v[0:3], v[88:91]
	v_mfma_f32_16x16x32_bf16 v[4:7], v[4:7], v[0:3], v[92:95]
	v_mfma_f32_16x16x32_bf16 v[0:3], v[120:123], v[0:3], v[96:99]
	s_cbranch_scc1 .LBB0_56
	s_lshl_b32 s0, s43, 4
	s_and_b32 s0, s0, 0x70
	s_bfe_u32 s1, s43, 0x40003
	s_or_b32 s1, s0, s1
	v_lshl_add_u32 v72, s1, 7, v79
	s_and_b32 s0, s43, 0xffffff80
	v_ashrrev_i32_e32 v73, 31, v72
	v_readlane_b32 s48, v245, 4
	s_ashr_i32 s1, s0, 31
	v_lshlrev_b64 v[80:81], 12, v[72:73]
	v_readlane_b32 s49, v245, 5
	s_lshl_b64 s[0:1], s[0:1], 2
	s_mov_b32 s22, 0x3fb504f3
	v_lshl_add_u64 v[80:81], s[48:49], 0, v[80:81]
	v_lshl_add_u64 v[80:81], v[80:81], 0, s[0:1]
	v_lshl_add_u64 v[80:81], v[80:81], 0, s[2:3]
	v_lshl_add_u64 v[84:85], v[80:81], 0, v[142:143]
	v_mov_b32_e32 v138, v84
	v_mov_b32_e32 v139, v85
	global_load_dwordx4 v[126:129], v[138:139], off
	global_load_dwordx4 v[130:133], v[138:139], off offset:64
	global_load_dwordx4 v[134:137], v[138:139], off offset:128
	global_load_dwordx4 v[146:149], v[138:139], off offset:192
	v_add_co_u32_e32 v138, vcc, 0x10000, v138
	s_nop 1
	v_addc_co_u32_e32 v139, vcc, 0, v139, vcc
	global_load_dwordx4 v[150:153], v[138:139], off
	global_load_dwordx4 v[154:157], v[138:139], off offset:64
	global_load_dwordx4 v[158:161], v[138:139], off offset:128
	global_load_dwordx4 v[162:165], v[138:139], off offset:192
	v_add_co_u32_e32 v138, vcc, 0x10000, v138
	s_nop 1
	v_addc_co_u32_e32 v139, vcc, 0, v139, vcc
	global_load_dwordx4 v[166:169], v[138:139], off
	global_load_dwordx4 v[202:205], v[138:139], off offset:64
	global_load_dwordx4 v[206:209], v[138:139], off offset:128
	global_load_dwordx4 v[216:219], v[138:139], off offset:192
	v_add_co_u32_e32 v138, vcc, 0x10000, v138
	s_nop 1
	v_addc_co_u32_e32 v139, vcc, 0, v139, vcc
	global_load_dwordx4 v[220:223], v[138:139], off
	global_load_dwordx4 v[224:227], v[138:139], off offset:64
	global_load_dwordx4 v[228:231], v[138:139], off offset:128
	global_load_dwordx4 v[232:235], v[138:139], off offset:192
	s_add_i32 s43, s43, s4
	v_readlane_b32 s50, v245, 6
	v_readlane_b32 s51, v245, 7
	v_readlane_b32 s52, v245, 8
	v_readlane_b32 s53, v245, 9
	v_readlane_b32 s54, v245, 10
	v_readlane_b32 s55, v245, 11
	s_waitcnt vmcnt(15)
	v_pk_mul_f32 v[126:127], v[126:127], s[22:23] op_sel_hi:[1,0]
	s_nop 0
	v_pk_fma_f32 v[60:61], v[60:61], 0.5, v[126:127] op_sel_hi:[1,0,1]
	v_pk_mul_f32 v[126:127], v[128:129], s[22:23] op_sel_hi:[1,0]
	s_nop 0
	v_pk_fma_f32 v[62:63], v[62:63], 0.5, v[126:127] op_sel_hi:[1,0,1]
	global_store_dwordx4 v[84:85], v[60:63], off
	s_waitcnt vmcnt(15)
	v_pk_mul_f32 v[130:131], v[130:131], s[22:23] op_sel_hi:[1,0]
	s_nop 0
	v_pk_fma_f32 v[56:57], v[56:57], 0.5, v[130:131] op_sel_hi:[1,0,1]
	v_pk_mul_f32 v[130:131], v[132:133], s[22:23] op_sel_hi:[1,0]
	s_nop 0
	v_pk_fma_f32 v[58:59], v[58:59], 0.5, v[130:131] op_sel_hi:[1,0,1]
	global_store_dwordx4 v[84:85], v[56:59], off offset:64
	s_waitcnt vmcnt(15)
; template <int EPI>
; DI void gemm_epilogue(f32x4 (&acc)[4][4], int m0, int n0, int wm, int wn, int l15, int quad, const EpiArgs& e) {
;     ...
;     } else {
;       float4 rv[4];
; #pragma unroll
;       for (int nt = 0; nt < 4; ++nt) rv[nt] = *(const float4*)(e.resid + row * D_ + n0 + wn * 64 + nt * 16 + 4 * quad);
; #pragma unroll
;       for (int nt = 0; nt < 4; ++nt) { const f32x4 a = acc[mt][nt];
;         *(float4*)(e.of32 + row * D_ + n0 + wn * 64 + nt * 16 + 4 * quad) = (float4){e.alpha * rv[nt].x + e.sc * a[0], e.alpha * rv[nt].y + e.sc * a[1], e.alpha * rv[nt].z + e.sc * a[2], e.alpha * rv[nt].w + e.sc * a[3]}; }
	v_pk_mul_f32 v[134:135], v[134:135], s[22:23] op_sel_hi:[1,0]
	s_nop 0
	v_pk_fma_f32 v[52:53], v[52:53], 0.5, v[134:135] op_sel_hi:[1,0,1]
	v_pk_mul_f32 v[134:135], v[136:137], s[22:23] op_sel_hi:[1,0]
	s_nop 0
	v_pk_fma_f32 v[54:55], v[54:55], 0.5, v[134:135] op_sel_hi:[1,0,1]
	global_store_dwordx4 v[84:85], v[52:55], off offset:128
	s_waitcnt vmcnt(15)
	v_pk_mul_f32 v[146:147], v[146:147], s[22:23] op_sel_hi:[1,0]
	s_nop 0
	v_pk_fma_f32 v[48:49], v[48:49], 0.5, v[146:147] op_sel_hi:[1,0,1]
	v_pk_mul_f32 v[146:147], v[148:149], s[22:23] op_sel_hi:[1,0]
	s_nop 0
	v_pk_fma_f32 v[50:51], v[50:51], 0.5, v[146:147] op_sel_hi:[1,0,1]
	global_store_dwordx4 v[84:85], v[48:51], off offset:192
	s_nop 1
	v_or_b32_e32 v48, 16, v72
	v_ashrrev_i32_e32 v49, 31, v48
	v_lshlrev_b64 v[48:49], 12, v[48:49]
	v_lshl_add_u64 v[48:49], s[48:49], 0, v[48:49]
	v_lshl_add_u64 v[48:49], v[48:49], 0, s[0:1]
	v_lshl_add_u64 v[48:49], v[48:49], 0, s[2:3]
	v_lshl_add_u64 v[52:53], v[48:49], 0, v[142:143]
	s_waitcnt vmcnt(15)
	v_pk_mul_f32 v[150:151], v[150:151], s[22:23] op_sel_hi:[1,0]
	s_nop 0
	v_pk_fma_f32 v[44:45], v[44:45], 0.5, v[150:151] op_sel_hi:[1,0,1]
	v_pk_mul_f32 v[150:151], v[152:153], s[22:23] op_sel_hi:[1,0]
	s_nop 0
	v_pk_fma_f32 v[46:47], v[46:47], 0.5, v[150:151] op_sel_hi:[1,0,1]
	global_store_dwordx4 v[52:53], v[44:47], off
	s_waitcnt vmcnt(15)
	v_pk_mul_f32 v[154:155], v[154:155], s[22:23] op_sel_hi:[1,0]
	s_nop 0
	v_pk_fma_f32 v[40:41], v[40:41], 0.5, v[154:155] op_sel_hi:[1,0,1]
	v_pk_mul_f32 v[154:155], v[156:157], s[22:23] op_sel_hi:[1,0]
	s_nop 0
	v_pk_fma_f32 v[42:43], v[42:43], 0.5, v[154:155] op_sel_hi:[1,0,1]
	global_store_dwordx4 v[52:53], v[40:43], off offset:64
	s_waitcnt vmcnt(15)
	v_pk_mul_f32 v[158:159], v[158:159], s[22:23] op_sel_hi:[1,0]
	s_nop 0
	v_pk_fma_f32 v[36:37], v[36:37], 0.5, v[158:159] op_sel_hi:[1,0,1]
	v_pk_mul_f32 v[158:159], v[160:161], s[22:23] op_sel_hi:[1,0]
	s_nop 0
	v_pk_fma_f32 v[38:39], v[38:39], 0.5, v[158:159] op_sel_hi:[1,0,1]
	global_store_dwordx4 v[52:53], v[36:39], off offset:128
	s_waitcnt vmcnt(15)
	v_pk_mul_f32 v[162:163], v[162:163], s[22:23] op_sel_hi:[1,0]
	s_nop 0
	v_pk_fma_f32 v[32:33], v[32:33], 0.5, v[162:163] op_sel_hi:[1,0,1]
	v_pk_mul_f32 v[162:163], v[164:165], s[22:23] op_sel_hi:[1,0]
	s_nop 0
	v_pk_fma_f32 v[34:35], v[34:35], 0.5, v[162:163] op_sel_hi:[1,0,1]
	global_store_dwordx4 v[52:53], v[32:35], off offset:192
	s_nop 1
	v_or_b32_e32 v32, 32, v72
	v_ashrrev_i32_e32 v33, 31, v32
	v_lshlrev_b64 v[32:33], 12, v[32:33]
	v_lshl_add_u64 v[32:33], s[48:49], 0, v[32:33]
	v_lshl_add_u64 v[32:33], v[32:33], 0, s[0:1]
	v_lshl_add_u64 v[32:33], v[32:33], 0, s[2:3]
	v_lshl_add_u64 v[36:37], v[32:33], 0, v[142:143]
	s_waitcnt vmcnt(15)
	v_pk_mul_f32 v[166:167], v[166:167], s[22:23] op_sel_hi:[1,0]
	s_nop 0
	v_pk_fma_f32 v[28:29], v[28:29], 0.5, v[166:167] op_sel_hi:[1,0,1]
	v_pk_mul_f32 v[166:167], v[168:169], s[22:23] op_sel_hi:[1,0]
	s_nop 0
	v_pk_fma_f32 v[30:31], v[30:31], 0.5, v[166:167] op_sel_hi:[1,0,1]
	global_store_dwordx4 v[36:37], v[28:31], off
	s_waitcnt vmcnt(15)
	v_pk_mul_f32 v[202:203], v[202:203], s[22:23] op_sel_hi:[1,0]
	s_nop 0
	v_pk_fma_f32 v[24:25], v[24:25], 0.5, v[202:203] op_sel_hi:[1,0,1]
	v_pk_mul_f32 v[202:203], v[204:205], s[22:23] op_sel_hi:[1,0]
	s_nop 0
	v_pk_fma_f32 v[26:27], v[26:27], 0.5, v[202:203] op_sel_hi:[1,0,1]
	global_store_dwordx4 v[36:37], v[24:27], off offset:64
	s_waitcnt vmcnt(15)
	v_pk_mul_f32 v[206:207], v[206:207], s[22:23] op_sel_hi:[1,0]
	s_nop 0
	v_pk_fma_f32 v[20:21], v[20:21], 0.5, v[206:207] op_sel_hi:[1,0,1]
	v_pk_mul_f32 v[206:207], v[208:209], s[22:23] op_sel_hi:[1,0]
	s_nop 0
	v_pk_fma_f32 v[22:23], v[22:23], 0.5, v[206:207] op_sel_hi:[1,0,1]
	global_store_dwordx4 v[36:37], v[20:23], off offset:128
	s_waitcnt vmcnt(15)
; template <int EPI>
; DI void gemm_epilogue(f32x4 (&acc)[4][4], int m0, int n0, int wm, int wn, int l15, int quad, const EpiArgs& e) {
;     ...
;     } else {
;       float4 rv[4];
; #pragma unroll
;       for (int nt = 0; nt < 4; ++nt) rv[nt] = *(const float4*)(e.resid + row * D_ + n0 + wn * 64 + nt * 16 + 4 * quad);
; #pragma unroll
;       for (int nt = 0; nt < 4; ++nt) { const f32x4 a = acc[mt][nt];
;         *(float4*)(e.of32 + row * D_ + n0 + wn * 64 + nt * 16 + 4 * quad) = (float4){e.alpha * rv[nt].x + e.sc * a[0], e.alpha * rv[nt].y + e.sc * a[1], e.alpha * rv[nt].z + e.sc * a[2], e.alpha * rv[nt].w + e.sc * a[3]}; }
;     }
;   }
; #pragma unroll
;   for (int i = 0; i < 4; ++i)
; #pragma unroll
;     for (int j = 0; j < 4; ++j) acc[i][j] = (f32x4){0.f, 0.f, 0.f, 0.f};
	v_pk_mul_f32 v[216:217], v[216:217], s[22:23] op_sel_hi:[1,0]
	s_nop 0
	v_pk_fma_f32 v[16:17], v[16:17], 0.5, v[216:217] op_sel_hi:[1,0,1]
	v_pk_mul_f32 v[216:217], v[218:219], s[22:23] op_sel_hi:[1,0]
	s_nop 0
	v_pk_fma_f32 v[18:19], v[18:19], 0.5, v[216:217] op_sel_hi:[1,0,1]
	global_store_dwordx4 v[36:37], v[16:19], off offset:192
	s_nop 1
	v_or_b32_e32 v16, 48, v72
	v_ashrrev_i32_e32 v17, 31, v16
	v_lshlrev_b64 v[16:17], 12, v[16:17]
	v_lshl_add_u64 v[16:17], s[48:49], 0, v[16:17]
	v_lshl_add_u64 v[16:17], v[16:17], 0, s[0:1]
	v_lshl_add_u64 v[16:17], v[16:17], 0, s[2:3]
	v_lshl_add_u64 v[16:17], v[16:17], 0, v[142:143]
	s_mov_b32 s0, 0
	s_waitcnt vmcnt(15)
	v_pk_mul_f32 v[220:221], v[220:221], s[22:23] op_sel_hi:[1,0]
	s_nop 0
	v_pk_fma_f32 v[12:13], v[12:13], 0.5, v[220:221] op_sel_hi:[1,0,1]
	v_pk_mul_f32 v[220:221], v[222:223], s[22:23] op_sel_hi:[1,0]
	s_nop 0
	v_pk_fma_f32 v[14:15], v[14:15], 0.5, v[220:221] op_sel_hi:[1,0,1]
	global_store_dwordx4 v[16:17], v[12:15], off
	s_waitcnt vmcnt(15)
	v_pk_mul_f32 v[224:225], v[224:225], s[22:23] op_sel_hi:[1,0]
	s_nop 0
	v_pk_fma_f32 v[8:9], v[8:9], 0.5, v[224:225] op_sel_hi:[1,0,1]
	v_pk_mul_f32 v[224:225], v[226:227], s[22:23] op_sel_hi:[1,0]
	s_nop 0
	v_pk_fma_f32 v[10:11], v[10:11], 0.5, v[224:225] op_sel_hi:[1,0,1]
	global_store_dwordx4 v[16:17], v[8:11], off offset:64
	s_waitcnt vmcnt(15)
	v_pk_mul_f32 v[228:229], v[228:229], s[22:23] op_sel_hi:[1,0]
	s_nop 0
	v_pk_fma_f32 v[4:5], v[4:5], 0.5, v[228:229] op_sel_hi:[1,0,1]
	v_pk_mul_f32 v[228:229], v[230:231], s[22:23] op_sel_hi:[1,0]
	s_nop 0
	v_pk_fma_f32 v[6:7], v[6:7], 0.5, v[228:229] op_sel_hi:[1,0,1]
	global_store_dwordx4 v[16:17], v[4:7], off offset:128
	s_waitcnt vmcnt(15)
	v_pk_mul_f32 v[232:233], v[232:233], s[22:23] op_sel_hi:[1,0]
	s_nop 0
	v_pk_fma_f32 v[0:1], v[0:1], 0.5, v[232:233] op_sel_hi:[1,0,1]
	v_pk_mul_f32 v[232:233], v[234:235], s[22:23] op_sel_hi:[1,0]
	s_nop 0
	v_pk_fma_f32 v[2:3], v[2:3], 0.5, v[232:233] op_sel_hi:[1,0,1]
	global_store_dwordx4 v[16:17], v[0:3], off offset:192
	s_nop 1
	v_mov_b32_e32 v0, 0
	v_mov_b32_e32 v1, v0
	v_mov_b32_e32 v2, v0
	v_mov_b32_e32 v3, v0
	v_mov_b32_e32 v4, v0
	v_mov_b32_e32 v5, v0
	v_mov_b32_e32 v6, v0
	v_mov_b32_e32 v7, v0
	v_mov_b32_e32 v8, v0
	v_mov_b32_e32 v9, v0
	v_mov_b32_e32 v10, v0
	v_mov_b32_e32 v11, v0
	v_mov_b32_e32 v12, v0
	v_mov_b32_e32 v13, v0
	v_mov_b32_e32 v14, v0
	v_mov_b32_e32 v15, v0
	v_mov_b32_e32 v16, v0
	v_mov_b32_e32 v17, v0
	v_mov_b32_e32 v18, v0
	v_mov_b32_e32 v19, v0
	v_mov_b32_e32 v20, v0
	v_mov_b32_e32 v21, v0
	v_mov_b32_e32 v22, v0
	v_mov_b32_e32 v23, v0
	v_mov_b32_e32 v24, v0
	v_mov_b32_e32 v25, v0
	v_mov_b32_e32 v26, v0
	v_mov_b32_e32 v27, v0
	v_mov_b32_e32 v28, v0
	v_mov_b32_e32 v29, v0
	v_mov_b32_e32 v30, v0
	v_mov_b32_e32 v31, v0
	v_mov_b32_e32 v32, v0
	v_mov_b32_e32 v33, v0
	v_mov_b32_e32 v34, v0
	v_mov_b32_e32 v35, v0
	v_mov_b32_e32 v36, v0
	v_mov_b32_e32 v37, v0
	v_mov_b32_e32 v38, v0
	v_mov_b32_e32 v39, v0
	v_mov_b32_e32 v40, v0
	v_mov_b32_e32 v41, v0
	v_mov_b32_e32 v42, v0
	v_mov_b32_e32 v43, v0
	v_mov_b32_e32 v44, v0
	v_mov_b32_e32 v45, v0
	v_mov_b32_e32 v46, v0
	v_mov_b32_e32 v47, v0
	v_mov_b32_e32 v48, v0
	v_mov_b32_e32 v49, v0
	v_mov_b32_e32 v50, v0
	v_mov_b32_e32 v51, v0
	v_mov_b32_e32 v52, v0
	v_mov_b32_e32 v53, v0
	v_mov_b32_e32 v54, v0
	v_mov_b32_e32 v55, v0
	v_mov_b32_e32 v56, v0
	v_mov_b32_e32 v57, v0
	v_mov_b32_e32 v58, v0
	v_mov_b32_e32 v59, v0
	v_mov_b32_e32 v60, v0
	v_mov_b32_e32 v61, v0
	v_mov_b32_e32 v62, v0
	v_mov_b32_e32 v63, v0
	s_branch .LBB0_56

; #define MFMA16(a, b, c) __builtin_amdgcn_mfma_f32_16x16x32_bf16((a), (b), (c), 0, 0, 0)
; template <int EPI>
; DI void gemm_epilogue(f32x4 (&acc)[4][4], int m0, int n0, int wm, int wn, int l15, int quad, const EpiArgs& e) {
;     ...
;     } else {
;       float4 rv[4];
; #pragma unroll
;       for (int nt = 0; nt < 4; ++nt) rv[nt] = *(const float4*)(e.resid + row * D_ + n0 + wn * 64 + nt * 16 + 4 * quad);
; #pragma unroll
;       for (int nt = 0; nt < 4; ++nt) { const f32x4 a = acc[mt][nt];
;         *(float4*)(e.of32 + row * D_ + n0 + wn * 64 + nt * 16 + 4 * quad) = (float4){e.alpha * rv[nt].x + e.sc * a[0], e.alpha * rv[nt].y + e.sc * a[1], e.alpha * rv[nt].z + e.sc * a[2], e.alpha * rv[nt].w + e.sc * a[3]}; }
; DI void gemm_compute_sw(const bf16_t* sb, int wm, int wn, int l15, int quad, f32x4 (&acc)[4][4]) {
; #pragma unroll
;   for (int ks = 0; ks < 2; ++ks) {
;     bf16x8 af[4], bfr[4];
;     const int sl = ((ks * 4 + quad) ^ ((l15 >> 1) & 7)) * 8;
; #pragma unroll
;     for (int mt = 0; mt < 4; ++mt) af[mt] = *(const bf16x8*)(sb + (wm * 64 + mt * 16 + l15) * 64 + sl);
; #pragma unroll
;     for (int nt = 0; nt < 4; ++nt) bfr[nt] = *(const bf16x8*)(sb + 8192 + (wn * 64 + nt * 16 + l15) * 64 + sl);
; #pragma unroll
;     for (int mt = 0; mt < 4; ++mt)
; #pragma unroll
;       for (int nt = 0; nt < 4; ++nt) acc[mt][nt] = MFMA16(bfr[nt], af[mt], acc[mt][nt]);
;   }
; }
.LBB0_95:
	ds_read_b128 v[80:83], v76 offset:49152
	ds_read_b128 v[84:87], v75 offset:32768
	ds_read_b128 v[88:91], v76 offset:51200
	ds_read_b128 v[92:95], v76 offset:53248
	ds_read_b128 v[96:99], v76 offset:55296
	s_add_i32 s0, s0, 2
	s_waitcnt lgkmcnt(0)
	v_mfma_f32_16x16x32_bf16 v[16:19], v[80:83], v[84:87], v[16:19]
	s_cmp_lg_u32 s0, 16
	ds_read_b128 v[112:115], v78 offset:49152
	ds_read_b128 v[116:119], v78 offset:51200
	v_mfma_f32_16x16x32_bf16 v[4:7], v[88:91], v[84:87], v[4:7]
	ds_read_b128 v[120:123], v78 offset:55296
	v_mfma_f32_16x16x32_bf16 v[8:11], v[92:95], v[84:87], v[8:11]
	v_mfma_f32_16x16x32_bf16 v[12:15], v[96:99], v[84:87], v[12:15]
	ds_read_b128 v[84:87], v75 offset:34816
	s_waitcnt lgkmcnt(0)
	v_mfma_f32_16x16x32_bf16 v[0:3], v[80:83], v[84:87], v[0:3]
	v_mfma_f32_16x16x32_bf16 v[20:23], v[88:91], v[84:87], v[20:23]
	v_mfma_f32_16x16x32_bf16 v[24:27], v[92:95], v[84:87], v[24:27]
	v_mfma_f32_16x16x32_bf16 v[28:31], v[96:99], v[84:87], v[28:31]
	ds_read_b128 v[84:87], v75 offset:36864
	s_waitcnt lgkmcnt(0)
	v_mfma_f32_16x16x32_bf16 v[100:103], v[80:83], v[84:87], v[32:35]
	s_nop 2
	ds_read_b128 v[32:35], v75 offset:38912
	v_mfma_f32_16x16x32_bf16 v[104:107], v[88:91], v[84:87], v[36:39]
	v_mfma_f32_16x16x32_bf16 v[108:111], v[92:95], v[84:87], v[44:47]
	v_mfma_f32_16x16x32_bf16 v[84:87], v[96:99], v[84:87], v[52:55]
	s_waitcnt lgkmcnt(0)
	v_mfma_f32_16x16x32_bf16 v[80:83], v[80:83], v[32:35], v[40:43]
	v_mfma_f32_16x16x32_bf16 v[88:91], v[88:91], v[32:35], v[48:51]
	v_mfma_f32_16x16x32_bf16 v[92:95], v[92:95], v[32:35], v[60:63]
	v_mfma_f32_16x16x32_bf16 v[96:99], v[96:99], v[32:35], v[56:59]
	ds_read_b128 v[32:35], v77 offset:32768
	s_waitcnt lgkmcnt(0)
	v_mfma_f32_16x16x32_bf16 v[56:59], v[116:119], v[32:35], v[4:7]
	s_nop 2
	ds_read_b128 v[4:7], v78 offset:53248
	s_waitcnt lgkmcnt(0)
	v_mfma_f32_16x16x32_bf16 v[52:55], v[4:7], v[32:35], v[8:11]
	s_nop 2
	ds_read_b128 v[8:11], v77 offset:34816
	s_waitcnt lgkmcnt(0)
	v_mfma_f32_16x16x32_bf16 v[44:47], v[112:115], v[8:11], v[0:3]
	s_nop 2
	ds_read_b128 v[0:3], v77 offset:36864
	v_mfma_f32_16x16x32_bf16 v[60:63], v[112:115], v[32:35], v[16:19]
	v_mfma_f32_16x16x32_bf16 v[48:51], v[120:123], v[32:35], v[12:15]
	v_mfma_f32_16x16x32_bf16 v[40:43], v[116:119], v[8:11], v[20:23]
	v_mfma_f32_16x16x32_bf16 v[36:39], v[4:7], v[8:11], v[24:27]
	v_mfma_f32_16x16x32_bf16 v[32:35], v[120:123], v[8:11], v[28:31]
	s_waitcnt lgkmcnt(0)
	v_mfma_f32_16x16x32_bf16 v[28:31], v[112:115], v[0:3], v[100:103]
	v_mfma_f32_16x16x32_bf16 v[24:27], v[116:119], v[0:3], v[104:107]
	v_mfma_f32_16x16x32_bf16 v[20:23], v[4:7], v[0:3], v[108:111]
	v_mfma_f32_16x16x32_bf16 v[16:19], v[120:123], v[0:3], v[84:87]
	ds_read_b128 v[0:3], v77 offset:38912
	s_waitcnt vmcnt(0)
	s_waitcnt vmcnt(0) lgkmcnt(0)
	v_mfma_f32_16x16x32_bf16 v[12:15], v[112:115], v[0:3], v[80:83]
	s_barrier
	v_mfma_f32_16x16x32_bf16 v[8:11], v[116:119], v[0:3], v[88:91]
	v_mfma_f32_16x16x32_bf16 v[4:7], v[4:7], v[0:3], v[92:95]
	v_mfma_f32_16x16x32_bf16 v[0:3], v[120:123], v[0:3], v[96:99]
	s_cbranch_scc1 .LBB0_86
	s_lshl_b32 s0, s22, 4
	s_and_b32 s0, s0, 0x70
	s_bfe_u32 s1, s22, 0x40003
	s_or_b32 s1, s0, s1
	v_lshl_add_u32 v72, s1, 7, v79
	s_and_b32 s0, s22, 0xffffff80
	v_ashrrev_i32_e32 v73, 31, v72
	v_readlane_b32 s36, v245, 4
	s_ashr_i32 s1, s0, 31
	v_lshlrev_b64 v[80:81], 12, v[72:73]
	v_readlane_b32 s37, v245, 5
	s_lshl_b64 s[0:1], s[0:1], 2
	s_mov_b32 s24, 0x3fb504f3
	v_lshl_add_u64 v[80:81], s[36:37], 0, v[80:81]
	v_lshl_add_u64 v[80:81], v[80:81], 0, s[0:1]
	v_lshl_add_u64 v[80:81], v[80:81], 0, s[2:3]
	v_lshl_add_u64 v[84:85], v[80:81], 0, v[142:143]
	v_mov_b32_e32 v138, v84
	v_mov_b32_e32 v139, v85
	global_load_dwordx4 v[126:129], v[138:139], off
	global_load_dwordx4 v[130:133], v[138:139], off offset:64
	global_load_dwordx4 v[134:137], v[138:139], off offset:128
	global_load_dwordx4 v[146:149], v[138:139], off offset:192
	v_add_co_u32_e32 v138, vcc, 0x10000, v138
	s_nop 1
	v_addc_co_u32_e32 v139, vcc, 0, v139, vcc
	global_load_dwordx4 v[150:153], v[138:139], off
	global_load_dwordx4 v[154:157], v[138:139], off offset:64
	global_load_dwordx4 v[158:161], v[138:139], off offset:128
	global_load_dwordx4 v[162:165], v[138:139], off offset:192
	v_add_co_u32_e32 v138, vcc, 0x10000, v138
	s_nop 1
	v_addc_co_u32_e32 v139, vcc, 0, v139, vcc
	global_load_dwordx4 v[166:169], v[138:139], off
	global_load_dwordx4 v[202:205], v[138:139], off offset:64
	global_load_dwordx4 v[206:209], v[138:139], off offset:128
	global_load_dwordx4 v[216:219], v[138:139], off offset:192
	v_add_co_u32_e32 v138, vcc, 0x10000, v138
	s_nop 1
	v_addc_co_u32_e32 v139, vcc, 0, v139, vcc
	global_load_dwordx4 v[220:223], v[138:139], off
	global_load_dwordx4 v[224:227], v[138:139], off offset:64
	global_load_dwordx4 v[228:231], v[138:139], off offset:128
	global_load_dwordx4 v[232:235], v[138:139], off offset:192
	s_add_i32 s22, s22, s4
	v_readlane_b32 s38, v245, 6
	v_readlane_b32 s39, v245, 7
	v_readlane_b32 s40, v245, 8
	v_readlane_b32 s41, v245, 9
	v_readlane_b32 s42, v245, 10
	v_readlane_b32 s43, v245, 11
	s_waitcnt vmcnt(15)
	v_pk_fma_f32 v[60:61], v[126:127], s[24:25], v[60:61] op_sel_hi:[1,0,1]
	v_pk_fma_f32 v[62:63], v[128:129], s[24:25], v[62:63] op_sel_hi:[1,0,1]
	global_store_dwordx4 v[84:85], v[60:63], off
	s_waitcnt vmcnt(15)
	v_pk_fma_f32 v[56:57], v[130:131], s[24:25], v[56:57] op_sel_hi:[1,0,1]
	v_pk_fma_f32 v[58:59], v[132:133], s[24:25], v[58:59] op_sel_hi:[1,0,1]
	global_store_dwordx4 v[84:85], v[56:59], off offset:64
	s_waitcnt vmcnt(15)
; template <int EPI>
; DI void gemm_epilogue(f32x4 (&acc)[4][4], int m0, int n0, int wm, int wn, int l15, int quad, const EpiArgs& e) {
;     ...
;     } else {
;       float4 rv[4];
; #pragma unroll
;       for (int nt = 0; nt < 4; ++nt) rv[nt] = *(const float4*)(e.resid + row * D_ + n0 + wn * 64 + nt * 16 + 4 * quad);
; #pragma unroll
;       for (int nt = 0; nt < 4; ++nt) { const f32x4 a = acc[mt][nt];
;         *(float4*)(e.of32 + row * D_ + n0 + wn * 64 + nt * 16 + 4 * quad) = (float4){e.alpha * rv[nt].x + e.sc * a[0], e.alpha * rv[nt].y + e.sc * a[1], e.alpha * rv[nt].z + e.sc * a[2], e.alpha * rv[nt].w + e.sc * a[3]}; }
;     }
;   }
; #pragma unroll
;   for (int i = 0; i < 4; ++i)
; #pragma unroll
;     for (int j = 0; j < 4; ++j) acc[i][j] = (f32x4){0.f, 0.f, 0.f, 0.f};
	v_pk_fma_f32 v[52:53], v[134:135], s[24:25], v[52:53] op_sel_hi:[1,0,1]
	v_pk_fma_f32 v[54:55], v[136:137], s[24:25], v[54:55] op_sel_hi:[1,0,1]
	global_store_dwordx4 v[84:85], v[52:55], off offset:128
	s_waitcnt vmcnt(15)
	v_pk_fma_f32 v[48:49], v[146:147], s[24:25], v[48:49] op_sel_hi:[1,0,1]
	v_pk_fma_f32 v[50:51], v[148:149], s[24:25], v[50:51] op_sel_hi:[1,0,1]
	global_store_dwordx4 v[84:85], v[48:51], off offset:192
	s_nop 1
	v_or_b32_e32 v48, 16, v72
	v_ashrrev_i32_e32 v49, 31, v48
	v_lshlrev_b64 v[48:49], 12, v[48:49]
	v_lshl_add_u64 v[48:49], s[36:37], 0, v[48:49]
	v_lshl_add_u64 v[48:49], v[48:49], 0, s[0:1]
	v_lshl_add_u64 v[48:49], v[48:49], 0, s[2:3]
	v_lshl_add_u64 v[52:53], v[48:49], 0, v[142:143]
	s_waitcnt vmcnt(15)
	v_pk_fma_f32 v[44:45], v[150:151], s[24:25], v[44:45] op_sel_hi:[1,0,1]
	v_pk_fma_f32 v[46:47], v[152:153], s[24:25], v[46:47] op_sel_hi:[1,0,1]
	global_store_dwordx4 v[52:53], v[44:47], off
	s_waitcnt vmcnt(15)
	v_pk_fma_f32 v[40:41], v[154:155], s[24:25], v[40:41] op_sel_hi:[1,0,1]
	v_pk_fma_f32 v[42:43], v[156:157], s[24:25], v[42:43] op_sel_hi:[1,0,1]
	global_store_dwordx4 v[52:53], v[40:43], off offset:64
	s_waitcnt vmcnt(15)
	v_pk_fma_f32 v[36:37], v[158:159], s[24:25], v[36:37] op_sel_hi:[1,0,1]
	v_pk_fma_f32 v[38:39], v[160:161], s[24:25], v[38:39] op_sel_hi:[1,0,1]
	global_store_dwordx4 v[52:53], v[36:39], off offset:128
	s_waitcnt vmcnt(15)
	v_pk_fma_f32 v[32:33], v[162:163], s[24:25], v[32:33] op_sel_hi:[1,0,1]
	v_pk_fma_f32 v[34:35], v[164:165], s[24:25], v[34:35] op_sel_hi:[1,0,1]
	global_store_dwordx4 v[52:53], v[32:35], off offset:192
	s_nop 1
	v_or_b32_e32 v32, 32, v72
	v_ashrrev_i32_e32 v33, 31, v32
	v_lshlrev_b64 v[32:33], 12, v[32:33]
	v_lshl_add_u64 v[32:33], s[36:37], 0, v[32:33]
	v_lshl_add_u64 v[32:33], v[32:33], 0, s[0:1]
	v_lshl_add_u64 v[32:33], v[32:33], 0, s[2:3]
	v_lshl_add_u64 v[36:37], v[32:33], 0, v[142:143]
	s_waitcnt vmcnt(15)
	v_pk_fma_f32 v[28:29], v[166:167], s[24:25], v[28:29] op_sel_hi:[1,0,1]
	v_pk_fma_f32 v[30:31], v[168:169], s[24:25], v[30:31] op_sel_hi:[1,0,1]
	global_store_dwordx4 v[36:37], v[28:31], off
	s_waitcnt vmcnt(15)
	v_pk_fma_f32 v[24:25], v[202:203], s[24:25], v[24:25] op_sel_hi:[1,0,1]
	v_pk_fma_f32 v[26:27], v[204:205], s[24:25], v[26:27] op_sel_hi:[1,0,1]
	global_store_dwordx4 v[36:37], v[24:27], off offset:64
	s_waitcnt vmcnt(15)
	v_pk_fma_f32 v[20:21], v[206:207], s[24:25], v[20:21] op_sel_hi:[1,0,1]
	v_pk_fma_f32 v[22:23], v[208:209], s[24:25], v[22:23] op_sel_hi:[1,0,1]
	global_store_dwordx4 v[36:37], v[20:23], off offset:128
	s_waitcnt vmcnt(15)
	v_pk_fma_f32 v[16:17], v[216:217], s[24:25], v[16:17] op_sel_hi:[1,0,1]
	v_pk_fma_f32 v[18:19], v[218:219], s[24:25], v[18:19] op_sel_hi:[1,0,1]
	global_store_dwordx4 v[36:37], v[16:19], off offset:192
	s_nop 1
	v_or_b32_e32 v16, 48, v72
	v_ashrrev_i32_e32 v17, 31, v16
	v_lshlrev_b64 v[16:17], 12, v[16:17]
	v_lshl_add_u64 v[16:17], s[36:37], 0, v[16:17]
	v_lshl_add_u64 v[16:17], v[16:17], 0, s[0:1]
	v_lshl_add_u64 v[16:17], v[16:17], 0, s[2:3]
	v_lshl_add_u64 v[20:21], v[16:17], 0, v[142:143]
	s_mov_b32 s0, 0
	s_waitcnt vmcnt(15)
	v_pk_fma_f32 v[12:13], v[220:221], s[24:25], v[12:13] op_sel_hi:[1,0,1]
	v_pk_fma_f32 v[14:15], v[222:223], s[24:25], v[14:15] op_sel_hi:[1,0,1]
	global_store_dwordx4 v[20:21], v[12:15], off
	s_waitcnt vmcnt(15)
	v_pk_fma_f32 v[8:9], v[224:225], s[24:25], v[8:9] op_sel_hi:[1,0,1]
	v_pk_fma_f32 v[10:11], v[226:227], s[24:25], v[10:11] op_sel_hi:[1,0,1]
	global_store_dwordx4 v[20:21], v[8:11], off offset:64
	s_waitcnt vmcnt(15)
	v_pk_fma_f32 v[4:5], v[228:229], s[24:25], v[4:5] op_sel_hi:[1,0,1]
	v_pk_fma_f32 v[6:7], v[230:231], s[24:25], v[6:7] op_sel_hi:[1,0,1]
	global_store_dwordx4 v[20:21], v[4:7], off offset:128
	s_waitcnt vmcnt(15)
	v_pk_fma_f32 v[0:1], v[232:233], s[24:25], v[0:1] op_sel_hi:[1,0,1]
	v_pk_fma_f32 v[2:3], v[234:235], s[24:25], v[2:3] op_sel_hi:[1,0,1]
	global_store_dwordx4 v[20:21], v[0:3], off offset:192
	s_nop 1
	v_mov_b32_e32 v0, 0
	v_mov_b32_e32 v1, v0
	v_mov_b32_e32 v2, v0
	v_mov_b32_e32 v3, v0
	v_mov_b32_e32 v4, v0
	v_mov_b32_e32 v5, v0
	v_mov_b32_e32 v6, v0
	v_mov_b32_e32 v7, v0
	v_mov_b32_e32 v8, v0
	v_mov_b32_e32 v9, v0
	v_mov_b32_e32 v10, v0
	v_mov_b32_e32 v11, v0
	v_mov_b32_e32 v12, v0
	v_mov_b32_e32 v13, v0
	v_mov_b32_e32 v14, v0
	v_mov_b32_e32 v15, v0
	v_mov_b32_e32 v16, v0
	v_mov_b32_e32 v17, v0
	v_mov_b32_e32 v18, v0
	v_mov_b32_e32 v19, v0
	v_mov_b32_e32 v20, v0
	v_mov_b32_e32 v21, v0
	v_mov_b32_e32 v22, v0
	v_mov_b32_e32 v23, v0
	v_mov_b32_e32 v24, v0
	v_mov_b32_e32 v25, v0
	v_mov_b32_e32 v26, v0
	v_mov_b32_e32 v27, v0
	v_mov_b32_e32 v28, v0
	v_mov_b32_e32 v29, v0
	v_mov_b32_e32 v30, v0
	v_mov_b32_e32 v31, v0
	v_mov_b32_e32 v32, v0
	v_mov_b32_e32 v33, v0
	v_mov_b32_e32 v34, v0
	v_mov_b32_e32 v35, v0
	v_mov_b32_e32 v36, v0
	v_mov_b32_e32 v37, v0
	v_mov_b32_e32 v38, v0
	v_mov_b32_e32 v39, v0
	v_mov_b32_e32 v40, v0
	v_mov_b32_e32 v41, v0
	v_mov_b32_e32 v42, v0
	v_mov_b32_e32 v43, v0
	v_mov_b32_e32 v44, v0
	v_mov_b32_e32 v45, v0
	v_mov_b32_e32 v46, v0
	v_mov_b32_e32 v47, v0
	v_mov_b32_e32 v48, v0
	v_mov_b32_e32 v49, v0
	v_mov_b32_e32 v50, v0
	v_mov_b32_e32 v51, v0
	v_mov_b32_e32 v52, v0
	v_mov_b32_e32 v53, v0
	v_mov_b32_e32 v54, v0
	v_mov_b32_e32 v55, v0
	v_mov_b32_e32 v56, v0
	v_mov_b32_e32 v57, v0
	v_mov_b32_e32 v58, v0
	v_mov_b32_e32 v59, v0
	v_mov_b32_e32 v60, v0
	v_mov_b32_e32 v61, v0
	v_mov_b32_e32 v62, v0
	v_mov_b32_e32 v63, v0
	s_branch .LBB0_86
